# GEMM phase prologue issues all 14 stage loads before the first wait
# baseline (speedup 1.0000x reference)
.LBB0_799:
	v_readlane_b32 s10, v254, 20
	v_readlane_b32 s11, v254, 21
	s_and_b64 s[10:11], s[10:11], exec
	v_readlane_b32 s10, v254, 35
	s_movk_i32 s7, 0x1300
	v_readlane_b32 s11, v254, 36
	s_cselect_b32 s41, s7, 0xe00
	s_cselect_b32 s7, 0, 0x800
	s_cselect_b32 s42, 0xf0f, 0
	s_cselect_b32 s17, s11, 0
	s_cselect_b32 s16, s10, 0
	s_cselect_b32 s43, 18, -1
	s_and_b32 s18, s0, 3
	s_add_i32 m0, s37, 0x18000
	v_lshl_add_u64 v[8:9], v[8:9], 0, s[86:87]
	s_lshl_b32 s0, s1, 13
	s_lshl_b32 s12, s18, 12
	global_load_lds_dwordx4 v[8:9], off
	v_lshl_add_u64 v[6:7], v[6:7], 0, s[86:87]
	s_add_i32 m0, s37, 0x1a000
	s_add_i32 s44, s37, 0x8000
	s_add_i32 s45, s37, 0xa000
	global_load_lds_dwordx4 v[6:7], off
	v_lshl_add_u64 v[2:3], v[2:3], 0, s[86:87]
	s_mov_b32 m0, s44
	s_add_u32 s10, s28, 0x40080
	global_load_lds_dwordx4 v[2:3], off
	v_lshl_add_u64 v[2:3], v[4:5], 0, s[86:87]
	s_mov_b32 m0, s45
	s_addc_u32 s11, s29, 0
	global_load_lds_dwordx4 v[2:3], off
	s_add_i32 m0, s37, 0x1c000
	v_lshl_add_u64 v[2:3], s[10:11], 0, v[0:1]
	global_load_lds_dwordx4 v[2:3], off
	v_lshl_add_u64 v[2:3], s[10:11], 0, v[158:159]
	s_add_i32 m0, s37, 0x1e000
	v_lshlrev_b32_e32 v4, 2, v221
	global_load_lds_dwordx4 v[2:3], off
	s_waitcnt vmcnt(8)
	s_barrier
	v_lshlrev_b32_e32 v2, 4, v220
	s_cmpk_lt_u32 s5, 0x100
	v_readlane_b32 s14, v254, 10
	v_lshl_or_b32 v3, v221, 6, v2
	v_and_b32_e32 v4, 32, v4
	s_cselect_b64 s[10:11], -1, 0
	s_cmp_eq_u32 s18, 0
	v_readlane_b32 s15, v254, 11
	v_bitop3_b32 v224, s12, v3, v4 bitop3:0xf6
	s_cselect_b64 s[12:13], -1, 0
	s_ashr_i32 s47, s14, 31
	v_readlane_b32 s14, v254, 32
	v_readlane_b32 s15, v254, 33
	s_add_u32 s14, s14, s7
	s_addc_u32 s15, s15, 0
	s_lshl_b32 s51, s4, 3
	v_bitop3_b32 v7, v3, s0, v4 bitop3:0xde
	v_lshlrev_b32_e32 v4, 5, v220
	v_mov_b32_e32 v5, v1
	v_cvt_f32_ubyte0_e32 v3, s51
	v_lshl_add_u64 v[160:161], s[16:17], 0, v[4:5]
	v_rcp_iflag_f32_e32 v4, v3
	v_readlane_b32 s4, v254, 30
	v_mov_b32_e32 v3, v1
	v_readlane_b32 s5, v254, 31
	v_mul_f32_e32 v4, 0x4f7ffffe, v4
	v_cvt_u32_f32_e32 v4, v4
	v_lshl_add_u64 v[170:171], s[4:5], 0, v[2:3]
	v_lshlrev_b32_e32 v2, 14, v10
	v_and_b32_e32 v2, 0xffff8000, v2
	s_lshr_b32 s48, s92, 3
	v_lshl_add_u32 v2, v11, 11, v2
	v_and_b32_e32 v3, 1, v10
	s_and_b32 s49, s92, 6
	s_add_i32 s50, s48, 1
	v_lshl_or_b32 v2, v3, 6, v2
	s_cmp_lg_u64 s[16:17], 0
	v_lshl_add_u32 v172, v12, 1, v2
	v_lshlrev_b32_e32 v2, 14, v13
	s_cselect_b64 s[16:17], -1, 0
	s_sub_i32 s4, 0, s51
	v_readfirstlane_b32 s5, v4
	v_and_b32_e32 v2, 0xffff8000, v2
	s_waitcnt vmcnt(6)
	s_mul_i32 s4, s4, s5
	v_lshl_add_u32 v2, v14, 11, v2
	v_and_b32_e32 v3, 1, v13
	v_lshlrev_b32_e32 v6, 3, v220
	s_mul_hi_u32 s4, s5, s4
	v_lshl_or_b32 v2, v3, 6, v2
	s_mov_b32 s46, 0
	v_lshl_or_b32 v223, s1, 6, v221
	v_cmp_gt_u32_e64 s[0:1], 2, v220
	v_lshl_or_b32 v225, s18, 5, v6
	s_add_i32 s52, s5, s4
	v_mov_b32_e32 v173, v1
	v_lshl_add_u32 v174, v15, 1, v2
	v_mov_b32_e32 v175, v1
	v_add_u32_e32 v226, 0, v7
	s_barrier
	s_branch .LBB0_802

.LBB0_1330:
	s_add_i32 m0, s31, 0x18000
	v_lshl_add_u64 v[2:3], v[2:3], 0, s[86:87]
	global_load_lds_dwordx4 v[2:3], off
	v_lshl_add_u64 v[2:3], v[4:5], 0, s[86:87]
	s_add_i32 m0, s31, 0x1a000
	s_add_i32 s37, s31, 0x8000
	global_load_lds_dwordx4 v[2:3], off
	v_lshl_add_u64 v[2:3], v[10:11], 0, s[86:87]
	s_mov_b32 m0, s37
	s_add_i32 s38, s31, 0xa000
	global_load_lds_dwordx4 v[2:3], off
	v_lshl_add_u64 v[2:3], v[12:13], 0, s[86:87]
	s_mov_b32 m0, s38
	v_lshlrev_b32_e32 v4, 2, v221
	global_load_lds_dwordx4 v[2:3], off
	s_add_i32 m0, s31, 0x1c000
	v_lshl_add_u64 v[2:3], v[6:7], 0, s[86:87]
	global_load_lds_dwordx4 v[2:3], off
	v_lshl_add_u64 v[2:3], v[8:9], 0, s[86:87]
	s_add_i32 m0, s31, 0x1e000
	s_and_b32 s39, s5, 3
	global_load_lds_dwordx4 v[2:3], off
	s_waitcnt vmcnt(8)
	s_barrier
	v_lshlrev_b32_e32 v3, 4, v220
	s_lshr_b32 s40, s4, 6
	v_lshl_or_b32 v196, s1, 6, v221
	v_lshlrev_b32_e32 v2, 3, v220
	v_lshl_or_b32 v3, v221, 6, v3
	s_lshl_b32 s1, s1, 13
	v_and_b32_e32 v4, 32, v4
	v_bitop3_b32 v5, v3, s1, v4 bitop3:0xde
	s_lshl_b32 s1, s39, 12
	s_add_i32 s41, s40, -2
	v_lshl_or_b32 v198, s39, 5, v2
	v_add_u32_e32 v2, v19, v17
	v_bitop3_b32 v197, s1, v3, v4 bitop3:0xf6
	s_cmpk_lt_u32 s0, 0x100
	v_readlane_b32 s4, v254, 10
	v_add_lshl_u32 v2, v2, v18, 1
	v_mov_b32_e32 v3, v1
	s_waitcnt vmcnt(6)
	s_cselect_b64 s[16:17], -1, 0
	s_ashr_i32 s43, s4, 31
	v_lshl_add_u64 v[174:175], s[10:11], 0, v[2:3]
	v_add_u32_e32 v2, v16, v14
	s_cmp_lg_u64 s[2:3], 0
	v_add_lshl_u32 v2, v2, v15, 1
	s_mov_b32 s42, 0
	v_cmp_eq_u32_e64 s[0:1], 0, v220
	s_cselect_b64 s[18:19], -1, 0
	v_mov_b32_e32 v159, v158
	v_lshl_add_u64 v[176:177], s[10:11], 0, v[2:3]
	v_add_u32_e32 v199, 0, v5
	v_readlane_b32 s45, v253, 6
	s_mov_b32 s46, s76
	s_barrier
	v_readlane_b32 s5, v254, 11
	s_branch .LBB0_1333

.LBB0_1436:
	s_lshl_b32 s6, s6, 5
	s_and_b32 s9, s6, 0x60
	s_add_i32 m0, s23, 0x18000
	v_lshl_add_u64 v[8:9], v[8:9], 0, s[86:87]
	s_lshl_b32 s8, s1, 13
	s_lshl_b32 s10, s9, 7
	global_load_lds_dwordx4 v[8:9], off
	v_lshl_add_u64 v[6:7], v[6:7], 0, s[86:87]
	s_add_i32 m0, s23, 0x1a000
	s_add_i32 s29, s23, 0x8000
	s_add_i32 s30, s23, 0xa000
	global_load_lds_dwordx4 v[6:7], off
	v_lshl_add_u64 v[2:3], v[2:3], 0, s[86:87]
	s_mov_b32 m0, s29
	s_add_u32 s6, s16, 0x40080
	global_load_lds_dwordx4 v[2:3], off
	v_lshl_add_u64 v[2:3], v[4:5], 0, s[86:87]
	s_mov_b32 m0, s30
	s_addc_u32 s7, s17, 0
	global_load_lds_dwordx4 v[2:3], off
	s_add_i32 m0, s23, 0x1c000
	v_lshl_add_u64 v[2:3], s[6:7], 0, v[0:1]
	global_load_lds_dwordx4 v[2:3], off
	v_lshl_add_u64 v[2:3], s[6:7], 0, v[154:155]
	s_add_i32 m0, s23, 0x1e000
	v_lshlrev_b32_e32 v4, 2, v221
	global_load_lds_dwordx4 v[2:3], off
	s_waitcnt vmcnt(8)
	s_barrier
	v_lshlrev_b32_e32 v2, 4, v220
	v_lshl_or_b32 v193, s1, 6, v221
	v_lshl_or_b32 v3, v221, 6, v2
	v_and_b32_e32 v4, 32, v4
	s_cmpk_lt_u32 s0, 0x100
	v_readlane_b32 s0, v254, 30
	v_bitop3_b32 v5, v3, s8, v4 bitop3:0xde
	v_bitop3_b32 v195, s10, v3, v4 bitop3:0xf6
	v_mov_b32_e32 v3, v1
	v_readlane_b32 s1, v254, 31
	s_waitcnt vmcnt(6)
	s_cselect_b64 s[6:7], -1, 0
	v_lshl_or_b32 v198, v220, 3, s9
	v_lshl_add_u64 v[160:161], s[0:1], 0, v[2:3]
	v_lshlrev_b32_e32 v2, 14, v14
	v_and_b32_e32 v2, 0xffff8000, v2
	v_lshl_add_u32 v2, v13, 11, v2
	v_and_b32_e32 v3, 1, v14
	v_lshl_or_b32 v2, v3, 6, v2
	v_lshl_add_u32 v170, v15, 1, v2
	v_lshlrev_b32_e32 v2, 14, v10
	v_and_b32_e32 v2, 0xffff8000, v2
	v_lshl_add_u32 v2, v11, 11, v2
	v_and_b32_e32 v3, 1, v10
	v_readlane_b32 s0, v254, 10
	v_lshl_or_b32 v2, v3, 6, v2
	s_ashr_i32 s31, s0, 31
	v_mov_b32_e32 v171, v1
	v_lshl_add_u32 v172, v12, 1, v2
	v_mov_b32_e32 v173, v1
	s_mov_b32 s34, 0
	v_add_u32_e32 v199, 0, v5
	s_mov_b32 s35, s77
	s_mov_b32 s36, s78
	s_barrier
	v_readlane_b32 s1, v254, 11
	s_branch .LBB0_1439
